# K-loop: per-segment s_setprio flips deleted, one static s_setprio 1 for waves 4-7 before the loop (reset after); on top of v5
# speedup vs baseline: 1.0043x; 1.0043x over previous
.LBB0_343:
	v_readlane_b32 s4, v253, 40
	s_nop 3
	s_cmp_eq_u32 s4, 0
	s_cbranch_scc0 .Lmy_prio_done
	s_setprio 1

.LBB0_344:
	s_add_i32 s4, s2, 2
	s_add_u32 s5, s68, s0
	s_addc_u32 s3, s69, s1
	s_add_u32 s33, s86, s0
	s_addc_u32 s35, s87, s1
	s_add_i32 s47, 0, 0x10000
	s_cmp_eq_u32 s21, s2
	s_cselect_b32 s3, s65, s3
	s_cselect_b32 s2, s64, s5
	v_add_u32_e32 v17, s47, v237
	s_cselect_b32 s57, s67, s35
	s_cselect_b32 s56, s66, s33
	s_add_i32 s5, 0, 0x14000
	ds_read_b128 v[134:137], v17
	ds_read_b128 v[138:141], v17 offset:1024
	ds_read_b128 v[142:145], v17 offset:2048
	ds_read_b128 v[146:149], v17 offset:3072
	v_add_u32_e32 v17, s5, v237
	ds_read_b128 v[150:153], v17
	ds_read_b128 v[154:157], v17 offset:1024
	ds_read_b128 v[158:161], v17 offset:2048
	ds_read_b128 v[162:165], v17 offset:3072
	v_lshl_add_u64 v[170:171], s[68:69], 0, v[132:133]
	s_add_i32 m0, s37, 0xc000
	ds_read_b128 v[166:169], v240
	ds_read_b128 v[186:189], v240 offset:1024
	ds_read_b128 v[190:193], v240 offset:2048
	ds_read_b128 v[194:197], v240 offset:3072
	ds_read_b128 v[198:201], v240 offset:4096
	ds_read_b128 v[202:205], v240 offset:5120
	ds_read_b128 v[206:209], v240 offset:6144
	ds_read_b128 v[210:213], v240 offset:7168
	global_load_lds_dwordx4 v[170:171], off
	v_lshl_add_u64 v[170:171], s[68:69], 0, v[18:19]
	s_add_i32 m0, s37, 0xe000
	s_nop 0
	global_load_lds_dwordx4 v[170:171], off
	s_waitcnt vmcnt(8)
	s_waitcnt lgkmcnt(0)
	s_barrier
	s_waitcnt lgkmcnt(0)
	v_mfma_f32_16x16x32_bf16 v[8:11], v[134:137], v[166:169], v[8:11]
	v_mfma_f32_16x16x32_bf16 v[12:15], v[142:145], v[166:169], v[12:15]
	v_mfma_f32_16x16x32_bf16 v[28:31], v[134:137], v[190:193], v[28:31]
	v_mfma_f32_16x16x32_bf16 v[32:35], v[142:145], v[190:193], v[32:35]
	v_mfma_f32_16x16x32_bf16 v[36:39], v[134:137], v[198:201], v[36:39]
	v_mfma_f32_16x16x32_bf16 v[44:47], v[142:145], v[198:201], v[44:47]
	v_mfma_f32_16x16x32_bf16 v[80:83], v[134:137], v[206:209], v[80:83]
	v_mfma_f32_16x16x32_bf16 v[88:91], v[142:145], v[206:209], v[88:91]
	v_mfma_f32_16x16x32_bf16 v[8:11], v[138:141], v[186:189], v[8:11]
	v_mfma_f32_16x16x32_bf16 v[12:15], v[146:149], v[186:189], v[12:15]
	v_mfma_f32_16x16x32_bf16 v[28:31], v[138:141], v[194:197], v[28:31]
	v_mfma_f32_16x16x32_bf16 v[32:35], v[146:149], v[194:197], v[32:35]
	v_mfma_f32_16x16x32_bf16 v[36:39], v[138:141], v[202:205], v[36:39]
	v_mfma_f32_16x16x32_bf16 v[44:47], v[146:149], v[202:205], v[44:47]
	v_mfma_f32_16x16x32_bf16 v[80:83], v[138:141], v[210:213], v[80:83]
	v_mfma_f32_16x16x32_bf16 v[88:91], v[146:149], v[210:213], v[88:91]
	v_mfma_f32_16x16x32_bf16 v[0:3], v[150:153], v[166:169], v[0:3]
	v_mfma_f32_16x16x32_bf16 v[4:7], v[158:161], v[166:169], v[4:7]
	v_mfma_f32_16x16x32_bf16 v[20:23], v[150:153], v[190:193], v[20:23]
	v_mfma_f32_16x16x32_bf16 v[24:27], v[158:161], v[190:193], v[24:27]
	v_mfma_f32_16x16x32_bf16 v[40:43], v[150:153], v[198:201], v[40:43]
	v_mfma_f32_16x16x32_bf16 v[48:51], v[158:161], v[198:201], v[48:51]
	v_mfma_f32_16x16x32_bf16 v[60:63], v[150:153], v[206:209], v[60:63]
	v_mfma_f32_16x16x32_bf16 v[64:67], v[158:161], v[206:209], v[64:67]
	v_mfma_f32_16x16x32_bf16 v[0:3], v[154:157], v[186:189], v[0:3]
	v_mfma_f32_16x16x32_bf16 v[4:7], v[162:165], v[186:189], v[4:7]
	v_mfma_f32_16x16x32_bf16 v[20:23], v[154:157], v[194:197], v[20:23]
	v_mfma_f32_16x16x32_bf16 v[24:27], v[162:165], v[194:197], v[24:27]
	v_mfma_f32_16x16x32_bf16 v[40:43], v[154:157], v[202:205], v[40:43]
	v_mfma_f32_16x16x32_bf16 v[48:51], v[162:165], v[202:205], v[48:51]
	v_mfma_f32_16x16x32_bf16 v[60:63], v[154:157], v[210:213], v[60:63]
	v_mfma_f32_16x16x32_bf16 v[64:67], v[162:165], v[210:213], v[64:67]
	s_barrier
	s_add_i32 s33, s47, s17
	v_lshl_add_u64 v[170:171], s[56:57], 0, v[174:175]
	s_mov_b32 m0, s33
	ds_read_b128 v[166:169], v240 offset:16384
	ds_read_b128 v[186:189], v240 offset:17408
	ds_read_b128 v[190:193], v240 offset:18432
	ds_read_b128 v[194:197], v240 offset:19456
	ds_read_b128 v[198:201], v240 offset:20480
	ds_read_b128 v[202:205], v240 offset:21504
	ds_read_b128 v[206:209], v240 offset:22528
	ds_read_b128 v[210:213], v240 offset:23552
	global_load_lds_dwordx4 v[170:171], off
	s_add_i32 m0, s33, 0x2000
	v_lshl_add_u64 v[214:215], s[56:57], 0, v[178:179]
	s_add_u32 s56, s56, s36
	s_addc_u32 s57, s57, 0
	s_add_i32 s5, s5, s17
	global_load_lds_dwordx4 v[214:215], off
	v_lshl_add_u64 v[216:217], s[56:57], 0, v[174:175]
	s_mov_b32 m0, s5
	v_lshl_add_u64 v[224:225], s[56:57], 0, v[178:179]
	global_load_lds_dwordx4 v[216:217], off
	s_add_i32 m0, s5, 0x2000
	v_lshl_add_u64 v[226:227], s[2:3], 0, v[172:173]
	global_load_lds_dwordx4 v[224:225], off
	s_mov_b32 m0, s37
	v_lshl_add_u64 v[242:243], s[2:3], 0, v[176:177]
	global_load_lds_dwordx4 v[226:227], off
	s_mov_b32 m0, s45
	s_nop 0
	global_load_lds_dwordx4 v[242:243], off
	s_waitcnt vmcnt(8)
	s_waitcnt lgkmcnt(0)
	s_barrier
	s_waitcnt lgkmcnt(0)
	v_mfma_f32_16x16x32_bf16 v[68:71], v[134:137], v[166:169], v[68:71]
	v_mfma_f32_16x16x32_bf16 v[72:75], v[142:145], v[166:169], v[72:75]
	v_mfma_f32_16x16x32_bf16 v[92:95], v[134:137], v[190:193], v[92:95]
	v_mfma_f32_16x16x32_bf16 v[96:99], v[142:145], v[190:193], v[96:99]
	v_mfma_f32_16x16x32_bf16 v[108:111], v[134:137], v[198:201], v[108:111]
	v_mfma_f32_16x16x32_bf16 v[112:115], v[142:145], v[198:201], v[112:115]
	v_mfma_f32_16x16x32_bf16 v[124:127], v[134:137], v[206:209], v[124:127]
	v_mfma_f32_16x16x32_bf16 v[128:131], v[142:145], v[206:209], v[128:131]
	v_mfma_f32_16x16x32_bf16 v[68:71], v[138:141], v[186:189], v[68:71]
	v_mfma_f32_16x16x32_bf16 v[72:75], v[146:149], v[186:189], v[72:75]
	v_mfma_f32_16x16x32_bf16 v[92:95], v[138:141], v[194:197], v[92:95]
	v_mfma_f32_16x16x32_bf16 v[96:99], v[146:149], v[194:197], v[96:99]
	v_mfma_f32_16x16x32_bf16 v[108:111], v[138:141], v[202:205], v[108:111]
	v_mfma_f32_16x16x32_bf16 v[112:115], v[146:149], v[202:205], v[112:115]
	v_mfma_f32_16x16x32_bf16 v[124:127], v[138:141], v[210:213], v[124:127]
	v_mfma_f32_16x16x32_bf16 v[128:131], v[146:149], v[210:213], v[128:131]
	v_mfma_f32_16x16x32_bf16 v[52:55], v[150:153], v[166:169], v[52:55]
	v_mfma_f32_16x16x32_bf16 v[56:59], v[158:161], v[166:169], v[56:59]
	v_mfma_f32_16x16x32_bf16 v[76:79], v[150:153], v[190:193], v[76:79]
	v_mfma_f32_16x16x32_bf16 v[84:87], v[158:161], v[190:193], v[84:87]
	v_mfma_f32_16x16x32_bf16 v[100:103], v[150:153], v[198:201], v[100:103]
	v_mfma_f32_16x16x32_bf16 v[104:107], v[158:161], v[198:201], v[104:107]
	v_mfma_f32_16x16x32_bf16 v[116:119], v[150:153], v[206:209], v[116:119]
	v_mfma_f32_16x16x32_bf16 v[120:123], v[158:161], v[206:209], v[120:123]
	v_mfma_f32_16x16x32_bf16 v[52:55], v[154:157], v[186:189], v[52:55]
	v_mfma_f32_16x16x32_bf16 v[56:59], v[162:165], v[186:189], v[56:59]
	v_mfma_f32_16x16x32_bf16 v[76:79], v[154:157], v[194:197], v[76:79]
	v_mfma_f32_16x16x32_bf16 v[84:87], v[162:165], v[194:197], v[84:87]
	v_mfma_f32_16x16x32_bf16 v[100:103], v[154:157], v[202:205], v[100:103]
	v_mfma_f32_16x16x32_bf16 v[104:107], v[162:165], v[202:205], v[104:107]
	v_mfma_f32_16x16x32_bf16 v[116:119], v[154:157], v[210:213], v[116:119]
	v_mfma_f32_16x16x32_bf16 v[120:123], v[162:165], v[210:213], v[120:123]
	s_barrier
	s_add_i32 s5, 0, 0x18000
	v_add_u32_e32 v17, s5, v237
	s_add_i32 s33, 0, 0x1c000
	ds_read_b128 v[134:137], v17
	ds_read_b128 v[138:141], v17 offset:1024
	ds_read_b128 v[142:145], v17 offset:2048
	ds_read_b128 v[146:149], v17 offset:3072
	v_add_u32_e32 v17, s33, v237
	ds_read_b128 v[150:153], v17
	ds_read_b128 v[154:157], v17 offset:1024
	ds_read_b128 v[158:161], v17 offset:2048
	ds_read_b128 v[162:165], v17 offset:3072
	s_add_u32 s2, s2, s36
	s_addc_u32 s3, s3, 0
	s_mov_b32 m0, s26
	v_lshl_add_u64 v[244:245], s[2:3], 0, v[172:173]
	ds_read_b128 v[166:169], v240 offset:32768
	ds_read_b128 v[186:189], v240 offset:33792
	ds_read_b128 v[190:193], v240 offset:34816
	ds_read_b128 v[194:197], v240 offset:35840
	ds_read_b128 v[198:201], v240 offset:36864
	ds_read_b128 v[202:205], v240 offset:37888
	ds_read_b128 v[206:209], v240 offset:38912
	ds_read_b128 v[210:213], v240 offset:39936
	global_load_lds_dwordx4 v[244:245], off
	v_lshl_add_u64 v[244:245], s[2:3], 0, v[176:177]
	s_mov_b32 m0, s27
	s_nop 0
	global_load_lds_dwordx4 v[244:245], off
	s_waitcnt vmcnt(8)
	s_waitcnt lgkmcnt(0)
	s_barrier
	s_waitcnt lgkmcnt(0)
	v_mfma_f32_16x16x32_bf16 v[8:11], v[134:137], v[166:169], v[8:11]
	v_mfma_f32_16x16x32_bf16 v[12:15], v[142:145], v[166:169], v[12:15]
	v_mfma_f32_16x16x32_bf16 v[28:31], v[134:137], v[190:193], v[28:31]
	v_mfma_f32_16x16x32_bf16 v[32:35], v[142:145], v[190:193], v[32:35]
	v_mfma_f32_16x16x32_bf16 v[36:39], v[134:137], v[198:201], v[36:39]
	v_mfma_f32_16x16x32_bf16 v[44:47], v[142:145], v[198:201], v[44:47]
	v_mfma_f32_16x16x32_bf16 v[80:83], v[134:137], v[206:209], v[80:83]
	v_mfma_f32_16x16x32_bf16 v[88:91], v[142:145], v[206:209], v[88:91]
	v_mfma_f32_16x16x32_bf16 v[8:11], v[138:141], v[186:189], v[8:11]
	v_mfma_f32_16x16x32_bf16 v[12:15], v[146:149], v[186:189], v[12:15]
	v_mfma_f32_16x16x32_bf16 v[28:31], v[138:141], v[194:197], v[28:31]
	v_mfma_f32_16x16x32_bf16 v[32:35], v[146:149], v[194:197], v[32:35]
	v_mfma_f32_16x16x32_bf16 v[36:39], v[138:141], v[202:205], v[36:39]
	v_mfma_f32_16x16x32_bf16 v[44:47], v[146:149], v[202:205], v[44:47]
	v_mfma_f32_16x16x32_bf16 v[80:83], v[138:141], v[210:213], v[80:83]
	v_mfma_f32_16x16x32_bf16 v[88:91], v[146:149], v[210:213], v[88:91]
	v_mfma_f32_16x16x32_bf16 v[0:3], v[150:153], v[166:169], v[0:3]
	v_mfma_f32_16x16x32_bf16 v[4:7], v[158:161], v[166:169], v[4:7]
	v_mfma_f32_16x16x32_bf16 v[20:23], v[150:153], v[190:193], v[20:23]
	v_mfma_f32_16x16x32_bf16 v[24:27], v[158:161], v[190:193], v[24:27]
	v_mfma_f32_16x16x32_bf16 v[40:43], v[150:153], v[198:201], v[40:43]
	v_mfma_f32_16x16x32_bf16 v[48:51], v[158:161], v[198:201], v[48:51]
	v_mfma_f32_16x16x32_bf16 v[60:63], v[150:153], v[206:209], v[60:63]
	v_mfma_f32_16x16x32_bf16 v[64:67], v[158:161], v[206:209], v[64:67]
	v_mfma_f32_16x16x32_bf16 v[0:3], v[154:157], v[186:189], v[0:3]
	v_mfma_f32_16x16x32_bf16 v[4:7], v[162:165], v[186:189], v[4:7]
	v_mfma_f32_16x16x32_bf16 v[20:23], v[154:157], v[194:197], v[20:23]
	v_mfma_f32_16x16x32_bf16 v[24:27], v[162:165], v[194:197], v[24:27]
	v_mfma_f32_16x16x32_bf16 v[40:43], v[154:157], v[202:205], v[40:43]
	v_mfma_f32_16x16x32_bf16 v[48:51], v[162:165], v[202:205], v[48:51]
	v_mfma_f32_16x16x32_bf16 v[60:63], v[154:157], v[210:213], v[60:63]
	v_mfma_f32_16x16x32_bf16 v[64:67], v[162:165], v[210:213], v[64:67]
	s_barrier
	s_add_i32 s2, s5, s17
	v_lshl_add_u64 v[170:171], v[170:171], 0, s[6:7]
	s_mov_b32 m0, s2
	ds_read_b128 v[166:169], v240 offset:49152
	ds_read_b128 v[186:189], v240 offset:50176
	ds_read_b128 v[190:193], v240 offset:51200
	ds_read_b128 v[194:197], v240 offset:52224
	ds_read_b128 v[198:201], v240 offset:53248
	ds_read_b128 v[202:205], v240 offset:54272
	ds_read_b128 v[206:209], v240 offset:55296
	ds_read_b128 v[210:213], v240 offset:56320
	global_load_lds_dwordx4 v[170:171], off
	v_lshl_add_u64 v[170:171], v[214:215], 0, s[6:7]
	s_add_i32 m0, s2, 0x2000
	s_add_i32 s2, s33, s17
	global_load_lds_dwordx4 v[170:171], off
	v_lshl_add_u64 v[170:171], v[216:217], 0, s[6:7]
	s_mov_b32 m0, s2
	s_nop 0
	global_load_lds_dwordx4 v[170:171], off
	v_lshl_add_u64 v[170:171], v[224:225], 0, s[6:7]
	s_add_i32 m0, s2, 0x2000
	s_nop 0
	global_load_lds_dwordx4 v[170:171], off
	v_lshl_add_u64 v[170:171], v[226:227], 0, s[6:7]
	s_mov_b32 m0, s63
	s_nop 0
	global_load_lds_dwordx4 v[170:171], off
	v_lshl_add_u64 v[170:171], v[242:243], 0, s[6:7]
	s_mov_b32 m0, s20
	s_nop 0
	global_load_lds_dwordx4 v[170:171], off
	s_waitcnt vmcnt(8)
	s_waitcnt lgkmcnt(0)
	s_barrier
	s_waitcnt lgkmcnt(0)
	v_mfma_f32_16x16x32_bf16 v[68:71], v[134:137], v[166:169], v[68:71]
	v_mfma_f32_16x16x32_bf16 v[72:75], v[142:145], v[166:169], v[72:75]
	v_mfma_f32_16x16x32_bf16 v[92:95], v[134:137], v[190:193], v[92:95]
	v_mfma_f32_16x16x32_bf16 v[96:99], v[142:145], v[190:193], v[96:99]
	v_mfma_f32_16x16x32_bf16 v[108:111], v[134:137], v[198:201], v[108:111]
	v_mfma_f32_16x16x32_bf16 v[112:115], v[142:145], v[198:201], v[112:115]
	v_mfma_f32_16x16x32_bf16 v[124:127], v[134:137], v[206:209], v[124:127]
	v_mfma_f32_16x16x32_bf16 v[128:131], v[142:145], v[206:209], v[128:131]
	v_mfma_f32_16x16x32_bf16 v[68:71], v[138:141], v[186:189], v[68:71]
	v_mfma_f32_16x16x32_bf16 v[72:75], v[146:149], v[186:189], v[72:75]
	v_mfma_f32_16x16x32_bf16 v[92:95], v[138:141], v[194:197], v[92:95]
	v_mfma_f32_16x16x32_bf16 v[96:99], v[146:149], v[194:197], v[96:99]
	v_mfma_f32_16x16x32_bf16 v[108:111], v[138:141], v[202:205], v[108:111]
	v_mfma_f32_16x16x32_bf16 v[112:115], v[146:149], v[202:205], v[112:115]
	v_mfma_f32_16x16x32_bf16 v[124:127], v[138:141], v[210:213], v[124:127]
	v_mfma_f32_16x16x32_bf16 v[128:131], v[146:149], v[210:213], v[128:131]
	v_mfma_f32_16x16x32_bf16 v[52:55], v[150:153], v[166:169], v[52:55]
	v_mfma_f32_16x16x32_bf16 v[56:59], v[158:161], v[166:169], v[56:59]
	v_mfma_f32_16x16x32_bf16 v[76:79], v[150:153], v[190:193], v[76:79]
	v_mfma_f32_16x16x32_bf16 v[84:87], v[158:161], v[190:193], v[84:87]
	v_mfma_f32_16x16x32_bf16 v[100:103], v[150:153], v[198:201], v[100:103]
	v_mfma_f32_16x16x32_bf16 v[104:107], v[158:161], v[198:201], v[104:107]
	v_mfma_f32_16x16x32_bf16 v[116:119], v[150:153], v[206:209], v[116:119]
	v_mfma_f32_16x16x32_bf16 v[120:123], v[158:161], v[206:209], v[120:123]
	v_mfma_f32_16x16x32_bf16 v[52:55], v[154:157], v[186:189], v[52:55]
	v_mfma_f32_16x16x32_bf16 v[56:59], v[162:165], v[186:189], v[56:59]
	v_mfma_f32_16x16x32_bf16 v[76:79], v[154:157], v[194:197], v[76:79]
	v_mfma_f32_16x16x32_bf16 v[84:87], v[162:165], v[194:197], v[84:87]
	v_mfma_f32_16x16x32_bf16 v[100:103], v[154:157], v[202:205], v[100:103]
	v_mfma_f32_16x16x32_bf16 v[104:107], v[162:165], v[202:205], v[104:107]
	v_mfma_f32_16x16x32_bf16 v[116:119], v[154:157], v[210:213], v[116:119]
	v_mfma_f32_16x16x32_bf16 v[120:123], v[162:165], v[210:213], v[120:123]
	s_barrier
	s_add_u32 s0, s0, 0x100
	s_addc_u32 s1, s1, 0
	v_lshl_add_u64 v[132:133], v[132:133], 0, s[8:9]
	v_lshl_add_u64 v[18:19], v[18:19], 0, s[8:9]
	s_cmp_ge_u32 s4, s62
	s_mov_b32 s2, s4
	s_cbranch_scc0 .LBB0_344
	s_setprio 0
	v_readlane_b32 s0, v253, 40
	v_readlane_b32 s1, v253, 41
	s_and_b64 vcc, exec, s[0:1]
	s_cbranch_vccz .LBB0_347
	s_barrier
